# speedup vs baseline: 1.0682x; 1.0011x over previous
; #define LAS __attribute__((address_space(3)))
; DI void ssd_prompt_unit(const Args& a, int b, int hd, LAS unsigned char* lds, const int tid) {
;     ...
;     if (wave <= 4 && seg == 0) {
; #pragma unroll
;         for (int jj = 0; jj < 4; ++jj) { *(LAS f32x4*)(cwS + jj * 8) = *(const f32x4*)(a.in[16] + jj * 1536 + ch); *(LAS f32x4*)(cwS + jj * 8 + 4) = *(const f32x4*)(a.in[16] + jj * 1536 + ch + 4); }
;         *(LAS f32x4*)(cwS + 32) = *(const f32x4*)(a.in[17] + ch); *(LAS f32x4*)(cwS + 36) = *(const f32x4*)(a.in[17] + ch + 4);
;     }
.LBB0_252:
	s_andn2_saveexec_b64 s[0:1], s[0:1]
	s_lshl_b32 s2, s60, 6
	v_lshl_add_u32 v0, v9, 3, s2
	s_or_b64 exec, exec, s[0:1]
	s_movk_i32 s0, 0xa0
	v_and_b32_e32 v8, 63, v132
	v_mul_lo_u32 v2, v9, s0
	s_cmp_lt_i32 s70, 5
	s_cselect_b64 s[0:1], -1, 0
	v_cmp_gt_u32_e64 s[40:41], 8, v8
	v_add_u32_e32 v2, 0, v2
	s_and_b64 s[2:3], s[0:1], s[40:41]
	s_waitcnt lgkmcnt(0)
	v_ashrrev_i32_e32 v1, 31, v0
	v_add_u32_e32 v215, 0x1c400, v2
	s_and_saveexec_b64 s[0:1], s[2:3]
	s_cbranch_execz .LBB0_256
	v_readlane_b32 s72, v253, 59
	v_lshlrev_b64 v[6:7], 2, v[0:1]
	v_readlane_b32 s73, v253, 60
	v_readlane_b32 s2, v254, 52
	v_readlane_b32 s3, v254, 53
	v_lshl_add_u64 v[16:17], s[72:73], 0, v[6:7]
	global_load_dwordx4 v[24:27], v[16:17], off offset:16
	global_load_dwordx4 v[20:23], v[16:17], off
	v_readlane_b32 s74, v253, 61
	v_readlane_b32 s75, v253, 62
	v_readlane_b32 s82, v254, 5
	v_readlane_b32 s83, v254, 6
	v_readlane_b32 s82, v254, 40
	v_readlane_b32 s83, v254, 41
	v_readlane_b32 s76, v253, 63
	v_readlane_b32 s77, v254, 0
	v_readlane_b32 s78, v254, 1
	v_readlane_b32 s79, v254, 2
	v_readlane_b32 s80, v254, 3
	v_readlane_b32 s81, v254, 4
	v_readlane_b32 s84, v254, 7
	v_readlane_b32 s85, v254, 8
	v_readlane_b32 s86, v254, 9
	v_readlane_b32 s87, v254, 10
	v_lshl_add_u64 v[2:3], s[2:3], 0, v[6:7]
	global_load_dwordx4 v[28:31], v[2:3], off
	v_readlane_b32 s2, v254, 54
	v_readlane_b32 s3, v254, 55
	v_add_co_u32_e32 v2, vcc, 0x1000, v16
	s_nop 1
	v_addc_co_u32_e32 v3, vcc, 0, v17, vcc
	global_load_dwordx4 v[32:35], v[2:3], off offset:2064
	v_lshl_add_u64 v[2:3], s[2:3], 0, v[6:7]
	global_load_dwordx4 v[36:39], v[2:3], off
	v_readlane_b32 s2, v254, 56
	v_readlane_b32 s3, v254, 57
	v_add_co_u32_e32 v2, vcc, 0x3000, v16
	s_nop 1
	v_addc_co_u32_e32 v3, vcc, 0, v17, vcc
	global_load_dwordx4 v[40:43], v[2:3], off offset:16
	v_lshl_add_u64 v[2:3], s[2:3], 0, v[6:7]
	global_load_dwordx4 v[44:47], v[2:3], off
	v_lshl_add_u64 v[6:7], s[74:75], 0, v[6:7]
	v_add_co_u32_e32 v2, vcc, 0x4000, v16
	s_nop 1
	v_addc_co_u32_e32 v3, vcc, 0, v17, vcc
	global_load_dwordx4 v[48:51], v[2:3], off offset:2064
	global_load_dwordx4 v[56:59], v[6:7], off offset:16
	global_load_dwordx4 v[52:55], v[6:7], off
	s_waitcnt vmcnt(0)
	ds_write_b128 v215, v[20:23]
	ds_write_b128 v215, v[24:27] offset:16
	ds_write_b128 v215, v[28:31] offset:32
	ds_write_b128 v215, v[32:35] offset:48
	ds_write_b128 v215, v[36:39] offset:64
	ds_write_b128 v215, v[40:43] offset:80
	ds_write_b128 v215, v[44:47] offset:96
	ds_write_b128 v215, v[48:51] offset:112
	ds_write_b128 v215, v[52:55] offset:128
	ds_write_b128 v215, v[56:59] offset:144

; DI float lo16(unsigned w) { return __uint_as_float(w << 16); }
; DI float hi16(unsigned w) { return __uint_as_float(w & 0xffff0000u); }
; DI float rowscale(const float* ss, int row) {
;     const f32x4* p = (const f32x4*)(ss + (size_t)row * 16);
;     const f32x4 a = p[0], b = p[1], c = p[2], d = p[3];
;     const float s = (((a.x + a.y) + (a.z + a.w)) + ((b.x + b.y) + (b.z + b.w))) + (((c.x + c.y) + (c.z + c.w)) + ((d.x + d.y) + (d.z + d.w)));
;     return rsqrtf(s * (1.0f / 1024.0f) + EPS);
; }
; DI void rowscales8(const float* ss, int rowbase, int fr, int fq, float (&r)[2][4]) {
;     const int lane = fq * 16 + fr;
;     const float rA = rowscale(ss, rowbase + lane), rB = rowscale(ss, rowbase + 128 + lane);
; #pragma unroll
;     for (int m = 0; m < 4; ++m) { r[0][m] = __shfl(rA, m * 16 + fr); r[1][m] = __shfl(rB, m * 16 + fr); }
; }
;     DI void operator()(const pg8::f32x4 (&acc)[2][2][4][2], const pg8::Unit& u, int wr, int wc, int fr, int fq) const {
;         const int row0 = u.pm * 256 + wr * 64 + fr, col0 = u.pn * 256 + wc * 32 + 8 * fq;
;         float rs[2][4]; rowscales8(ss, u.pm * 256 + wr * 64, fr, fq, rs);
; #pragma unroll
;         for (int ai = 0; ai < 2; ++ai)
; #pragma unroll
;             for (int m = 0; m < 4; ++m) {
;                 const int row = row0 + ai * 128 + m * 16; const float r = rs[ai][m];
;                 float part = 0.f;
; #pragma unroll
;                 for (int bj = 0; bj < 2; ++bj) { const size_t off = (size_t)row * 1024 + col0 + bj * 128;
;                     const u32x4 tw = *(const u32x4*)(T + off); const u32x4 xw = *(const u32x4*)(xr + off);
;                     const pg8::f32x4 a0 = acc[ai][bj][m][0] * r, a1 = acc[ai][bj][m][1] * r;
;                     const float o0 = lo16(xw.x) + lo16(tw.x) * __frcp_rn(1.0f + __expf(-a0[0])), o1 = hi16(xw.x) + hi16(tw.x) * __frcp_rn(1.0f + __expf(-a0[1]));
.LBB0_470:
	s_lshl_b32 s1, s2, 8
	s_add_i32 s1, s1, s80
	v_or_b32_e32 v154, s1, v139
	v_ashrrev_i32_e32 v155, 31, v154
	v_lshlrev_b64 v[154:155], 6, v[154:155]
	v_lshl_add_u64 v[158:159], s[8:9], 0, v[154:155]
	global_load_dwordx4 v[154:157], v[158:159], off offset:16
	global_load_dwordx4 v[162:165], v[158:159], off offset:48
	global_load_dwordx4 v[166:169], v[158:159], off
	global_load_dwordx4 v[170:173], v[158:159], off offset:32
	v_add_u32_e32 v232, s1, v151
	v_ashrrev_i32_e32 v233, 31, v232
	v_lshlrev_b64 v[232:233], 6, v[232:233]
	v_lshl_add_u64 v[230:231], s[8:9], 0, v[232:233]
	global_load_dwordx4 v[214:217], v[230:231], off offset:16
	global_load_dwordx4 v[218:221], v[230:231], off offset:48
	global_load_dwordx4 v[222:225], v[230:231], off
	global_load_dwordx4 v[226:229], v[230:231], off offset:32
	s_mov_b32 s2, 0x3a800000
	v_or_b32_e32 v142, s1, v145
	v_lshl_or_b32 v140, s0, 8, v149
	s_waitcnt vmcnt(4)
	v_mov_b32_e32 v158, v166
	v_mov_b32_e32 v159, v170
	v_mov_b32_e32 v170, v167
	v_mov_b32_e32 v166, v168
	v_mov_b32_e32 v167, v172
	v_mov_b32_e32 v172, v169
	v_pk_add_f32 v[158:159], v[158:159], v[170:171]
	v_pk_add_f32 v[166:167], v[166:167], v[172:173]
	v_pk_add_f32 v[158:159], v[158:159], v[166:167]
	v_mov_b32_e32 v166, v154
	v_mov_b32_e32 v167, v162
	v_mov_b32_e32 v162, v155
	v_pk_add_f32 v[154:155], v[166:167], v[162:163]
	v_mov_b32_e32 v162, v156
	v_mov_b32_e32 v163, v164
	v_mov_b32_e32 v164, v157
	v_pk_add_f32 v[156:157], v[162:163], v[164:165]
	v_pk_add_f32 v[154:155], v[154:155], v[156:157]
	v_pk_add_f32 v[158:159], v[158:159], v[154:155]
	s_waitcnt vmcnt(0)
	v_mov_b64_e32 v[154:155], v[214:215]
	v_mov_b64_e32 v[156:157], v[216:217]
	v_mov_b64_e32 v[162:163], v[218:219]
	v_mov_b64_e32 v[164:165], v[220:221]
	v_mov_b64_e32 v[166:167], v[222:223]
	v_mov_b64_e32 v[168:169], v[224:225]
	v_mov_b64_e32 v[170:171], v[226:227]
	v_mov_b64_e32 v[172:173], v[228:229]
	v_mov_b32_e32 v174, v166
	v_mov_b32_e32 v175, v170
	v_mov_b32_e32 v170, v167
	v_pk_add_f32 v[166:167], v[174:175], v[170:171]
	v_mov_b32_e32 v170, v168
	v_mov_b32_e32 v171, v172
	v_mov_b32_e32 v172, v169
	v_pk_add_f32 v[168:169], v[170:171], v[172:173]
	v_pk_add_f32 v[166:167], v[166:167], v[168:169]
	v_mov_b32_e32 v168, v154
	v_mov_b32_e32 v169, v162
	v_mov_b32_e32 v162, v155
	v_pk_add_f32 v[154:155], v[168:169], v[162:163]
	v_mov_b32_e32 v162, v156
	v_mov_b32_e32 v163, v164
	v_mov_b32_e32 v164, v157
	v_pk_add_f32 v[156:157], v[162:163], v[164:165]
	v_pk_add_f32 v[154:155], v[154:155], v[156:157]
	v_mov_b32_e32 v157, v158
	v_pk_add_f32 v[154:155], v[166:167], v[154:155]
	v_mov_b32_e32 v156, v154
	v_mov_b32_e32 v158, v155
	v_pk_add_f32 v[154:155], v[156:157], v[158:159]
	v_pk_fma_f32 v[154:155], v[154:155], s[2:3], v[176:177] op_sel_hi:[1,0,0]
	v_mul_f32_e32 v138, 0x4b800000, v155
	v_cmp_gt_f32_e64 s[42:43], s39, v155
	v_cmp_gt_f32_e32 vcc, s39, v154
	s_nop 0
	v_cndmask_b32_e64 v138, v155, v138, s[42:43]
	v_rsq_f32_e32 v138, v138
	s_nop 0
	v_mul_f32_e32 v141, 0x45800000, v138
	v_cndmask_b32_e64 v138, v138, v141, s[42:43]
	v_mul_f32_e32 v141, 0x4b800000, v154
	v_cndmask_b32_e32 v141, v154, v141, vcc
	v_rsq_f32_e32 v141, v141
	s_lshl_b32 s42, s0, 2
	s_ashr_i32 s43, s42, 31
	v_mul_f32_e32 v143, 0x45800000, v141
	v_cndmask_b32_e32 v141, v141, v143, vcc
	v_and_b32_e32 v143, 64, v177
	v_or_b32_e32 v144, v143, v145
	v_lshlrev_b32_e32 v155, 2, v144
	ds_bpermute_b32 v168, v155, v138
	ds_bpermute_b32 v148, v155, v141
	ds_bpermute_b32 v154, v155, v138 offset:64
	ds_bpermute_b32 v146, v155, v141 offset:64
	ds_bpermute_b32 v152, v155, v138 offset:128
	ds_bpermute_b32 v144, v155, v141 offset:128
	ds_bpermute_b32 v150, v155, v138 offset:192
	ds_bpermute_b32 v138, v155, v141 offset:192
	v_xor_b32_e32 v155, 16, v177
	v_add_u32_e32 v143, 64, v143
	v_cmp_lt_i32_e32 vcc, v155, v143
	v_ashrrev_i32_e32 v141, 31, v140
	s_nop 0
	v_cndmask_b32_e32 v155, v177, v155, vcc
	v_lshlrev_b32_e32 v169, 2, v155
	v_xor_b32_e32 v155, 32, v177
	v_cmp_lt_i32_e32 vcc, v155, v143
	s_waitcnt lgkmcnt(7)
	v_pk_mul_f32 v[124:125], v[124:125], v[168:169] op_sel_hi:[1,0]
	v_pk_mul_f32 v[126:127], v[126:127], v[168:169] op_sel_hi:[1,0]
	v_cndmask_b32_e32 v143, v177, v155, vcc
	v_lshlrev_b32_e32 v155, 2, v143
	v_ashrrev_i32_e32 v143, 31, v142
	v_lshlrev_b64 v[156:157], 10, v[142:143]
	v_lshl_add_u64 v[156:157], v[156:157], 0, v[140:141]
	v_lshlrev_b64 v[158:159], 1, v[156:157]
	v_lshl_add_u64 v[156:157], s[18:19], 0, v[158:159]
	global_load_dwordx4 v[162:165], v[156:157], off
	v_lshl_add_u64 v[170:171], s[12:13], 0, v[158:159]
	global_load_dwordx4 v[172:175], v[170:171], off
	v_mul_f32_e32 v124, 0xbfb8aa3b, v124
	v_mul_f32_e32 v125, 0xbfb8aa3b, v125
	v_exp_f32_e32 v124, v124
	v_exp_f32_e32 v125, v125
	v_mul_f32_e32 v126, 0xbfb8aa3b, v126
	v_mul_f32_e32 v127, 0xbfb8aa3b, v127
	v_exp_f32_e32 v126, v126
	v_pk_add_f32 v[124:125], v[124:125], 1.0 op_sel_hi:[1,0]
	v_exp_f32_e32 v127, v127
	v_pk_mul_f32 v[120:121], v[120:121], v[168:169] op_sel_hi:[1,0]
	v_pk_mul_f32 v[122:123], v[122:123], v[168:169] op_sel_hi:[1,0]
	v_mul_f32_e32 v120, 0xbfb8aa3b, v120
	v_pk_add_f32 v[126:127], v[126:127], 1.0 op_sel_hi:[1,0]
	v_mul_f32_e32 v121, 0xbfb8aa3b, v121
	v_exp_f32_e32 v120, v120
	v_exp_f32_e32 v121, v121
	v_pk_mul_f32 v[116:117], v[116:117], v[168:169] op_sel_hi:[1,0]
	v_pk_mul_f32 v[118:119], v[118:119], v[168:169] op_sel_hi:[1,0]
	v_pk_mul_f32 v[114:115], v[114:115], v[168:169] op_sel_hi:[1,0]
	v_pk_add_f32 v[120:121], v[120:121], 1.0 op_sel_hi:[1,0]
	v_mul_f32_e32 v114, 0xbfb8aa3b, v114
	v_mul_f32_e32 v115, 0xbfb8aa3b, v115
	v_exp_f32_e32 v114, v114
	v_exp_f32_e32 v115, v115
	s_waitcnt vmcnt(1)
; DI unsigned pk2(float lo, float hi) { const f32x2_t v = {lo, hi}; const bf16x2_t b = __builtin_convertvector(v, bf16x2_t); return __builtin_bit_cast(unsigned, b); }
; DI float lo16(unsigned w) { return __uint_as_float(w << 16); }
; DI float hi16(unsigned w) { return __uint_as_float(w & 0xffff0000u); }
;     DI void operator()(const pg8::f32x4 (&acc)[2][2][4][2], const pg8::Unit& u, int wr, int wc, int fr, int fq) const {
;     ...
;                 for (int bj = 0; bj < 2; ++bj) { const size_t off = (size_t)row * 1024 + col0 + bj * 128;
;                     const u32x4 tw = *(const u32x4*)(T + off); const u32x4 xw = *(const u32x4*)(xr + off);
;                     const pg8::f32x4 a0 = acc[ai][bj][m][0] * r, a1 = acc[ai][bj][m][1] * r;
;                     const float o0 = lo16(xw.x) + lo16(tw.x) * __frcp_rn(1.0f + __expf(-a0[0])), o1 = hi16(xw.x) + hi16(tw.x) * __frcp_rn(1.0f + __expf(-a0[1]));
;                     const float o2 = lo16(xw.y) + lo16(tw.y) * __frcp_rn(1.0f + __expf(-a0[2])), o3 = hi16(xw.y) + hi16(tw.y) * __frcp_rn(1.0f + __expf(-a0[3]));
;                     const float o4 = lo16(xw.z) + lo16(tw.z) * __frcp_rn(1.0f + __expf(-a1[0])), o5 = hi16(xw.z) + hi16(tw.z) * __frcp_rn(1.0f + __expf(-a1[1]));
;                     const float o6 = lo16(xw.w) + lo16(tw.w) * __frcp_rn(1.0f + __expf(-a1[2])), o7 = hi16(xw.w) + hi16(tw.w) * __frcp_rn(1.0f + __expf(-a1[3]));
;                     u32x4 w; w.x = pk2(o0, o1); w.y = pk2(o2, o3); w.z = pk2(o4, o5); w.w = pk2(o6, o7); *(u32x4*)(xbo + off) = w;
;                     part += ((o0 * o0 + o1 * o1) + (o2 * o2 + o3 * o3)) + ((o4 * o4 + o5 * o5) + (o6 * o6 + o7 * o7)); }
;                 part += __shfl_xor(part, 16); part += __shfl_xor(part, 32);
;                 if (ssout && fq == 0) ssout[(size_t)row * 16 + u.pn * 4 + wc] = part;
	v_lshlrev_b32_e32 v166, 16, v162
	v_and_b32_e32 v167, 0xffff0000, v162
	s_waitcnt vmcnt(0)
	v_lshlrev_b32_e32 v158, 16, v172
	v_and_b32_e32 v159, 0xffff0000, v172
	v_pk_add_f32 v[114:115], v[114:115], 1.0 op_sel_hi:[1,0]
	v_rcp_f32_e32 v125, v125
	v_rcp_f32_e32 v124, v124
	s_nop 0
	v_pk_fma_f32 v[124:125], v[124:125], v[166:167], v[158:159]
	v_lshlrev_b32_e32 v158, 16, v173
	v_and_b32_e32 v159, 0xffff0000, v173
	v_lshlrev_b32_e32 v162, 16, v163
	v_rcp_f32_e32 v127, v127
	v_and_b32_e32 v163, 0xffff0000, v163
	v_rcp_f32_e32 v126, v126
	s_nop 0
	v_pk_fma_f32 v[126:127], v[126:127], v[162:163], v[158:159]
	v_lshlrev_b32_e32 v162, 16, v164
	v_and_b32_e32 v163, 0xffff0000, v164
	v_lshlrev_b32_e32 v158, 16, v174
	v_and_b32_e32 v159, 0xffff0000, v174
	v_rcp_f32_e32 v121, v121
	v_rcp_f32_e32 v120, v120
	s_nop 0
	v_pk_fma_f32 v[166:167], v[120:121], v[162:163], v[158:159]
	v_mul_f32_e32 v120, 0xbfb8aa3b, v122
	v_mul_f32_e32 v121, 0xbfb8aa3b, v123
	v_exp_f32_e32 v120, v120
	v_exp_f32_e32 v121, v121
	v_lshlrev_b32_e32 v158, 16, v165
	v_and_b32_e32 v159, 0xffff0000, v165
	v_lshlrev_b32_e32 v122, 16, v175
	v_pk_add_f32 v[120:121], v[120:121], 1.0 op_sel_hi:[1,0]
	v_and_b32_e32 v123, 0xffff0000, v175
	v_rcp_f32_e32 v121, v121
	v_rcp_f32_e32 v120, v120
	s_nop 0
	v_pk_fma_f32 v[172:173], v[120:121], v[158:159], v[122:123]
	v_cvt_pk_bf16_f32 v120, v124, v125
	v_cvt_pk_bf16_f32 v121, v126, v127
	v_cvt_pk_bf16_f32 v122, v166, v167
	v_cvt_pk_bf16_f32 v123, v172, v173
	global_store_dwordx4 v[156:157], v[120:123], off
	v_pk_mul_f32 v[158:159], v[124:125], v[124:125]
	v_pk_mul_f32 v[162:163], v[126:127], v[126:127]
	global_load_dwordx4 v[120:123], v[156:157], off offset:256
	global_load_dwordx4 v[124:127], v[170:171], off offset:256
	v_pk_mul_f32 v[170:171], v[112:113], v[168:169] op_sel_hi:[1,0]
	v_mul_f32_e32 v112, 0xbfb8aa3b, v116
	v_mul_f32_e32 v113, 0xbfb8aa3b, v117
	v_exp_f32_e32 v112, v112
	v_exp_f32_e32 v113, v113
	v_pk_mul_f32 v[164:165], v[166:167], v[166:167]
	v_pk_mul_f32 v[166:167], v[172:173], v[172:173]
	v_pk_add_f32 v[112:113], v[112:113], 1.0 op_sel_hi:[1,0]
	s_waitcnt vmcnt(1)
	v_lshlrev_b32_e32 v172, 16, v120
	v_and_b32_e32 v173, 0xffff0000, v120
	s_waitcnt vmcnt(0)
	v_lshlrev_b32_e32 v116, 16, v124
	v_and_b32_e32 v117, 0xffff0000, v124
	v_rcp_f32_e32 v113, v113
	v_rcp_f32_e32 v112, v112
	s_nop 0
	v_pk_fma_f32 v[112:113], v[112:113], v[172:173], v[116:117]
	v_mul_f32_e32 v116, 0xbfb8aa3b, v118
	v_mul_f32_e32 v117, 0xbfb8aa3b, v119
	v_exp_f32_e32 v116, v116
	v_exp_f32_e32 v117, v117
	v_lshlrev_b32_e32 v118, 16, v125
	v_and_b32_e32 v119, 0xffff0000, v125
	v_lshlrev_b32_e32 v120, 16, v121
	v_pk_add_f32 v[116:117], v[116:117], 1.0 op_sel_hi:[1,0]
	v_and_b32_e32 v121, 0xffff0000, v121
	v_rcp_f32_e32 v117, v117
	v_rcp_f32_e32 v116, v116
	s_nop 0
	v_pk_fma_f32 v[116:117], v[116:117], v[120:121], v[118:119]
	v_mul_f32_e32 v118, 0xbfb8aa3b, v170
	v_mul_f32_e32 v119, 0xbfb8aa3b, v171
	v_exp_f32_e32 v118, v118
	v_exp_f32_e32 v119, v119
	v_lshlrev_b32_e32 v124, 16, v122
	v_and_b32_e32 v125, 0xffff0000, v122
	v_lshlrev_b32_e32 v120, 16, v126
	v_pk_add_f32 v[118:119], v[118:119], 1.0 op_sel_hi:[1,0]
	v_and_b32_e32 v121, 0xffff0000, v126
	v_rcp_f32_e32 v119, v119
	v_rcp_f32_e32 v118, v118
	s_nop 0
	v_pk_fma_f32 v[124:125], v[118:119], v[124:125], v[120:121]
	v_lshlrev_b32_e32 v120, 16, v123
	v_and_b32_e32 v121, 0xffff0000, v123
	v_lshlrev_b32_e32 v118, 16, v127
	v_and_b32_e32 v119, 0xffff0000, v127
	v_rcp_f32_e32 v115, v115
	v_rcp_f32_e32 v114, v114
	s_nop 0
	v_pk_fma_f32 v[114:115], v[114:115], v[120:121], v[118:119]
	v_cvt_pk_bf16_f32 v118, v112, v113
	v_cvt_pk_bf16_f32 v119, v116, v117
	v_cvt_pk_bf16_f32 v120, v124, v125
	v_cvt_pk_bf16_f32 v121, v114, v115
	global_store_dwordx4 v[156:157], v[118:121], off offset:256
	v_pk_mul_f32 v[114:115], v[114:115], v[114:115]
	v_pk_mul_f32 v[112:113], v[112:113], v[112:113]
	v_pk_mul_f32 v[118:119], v[124:125], v[124:125]
	v_pk_mul_f32 v[116:117], v[116:117], v[116:117]
	v_add_f32_e32 v120, v166, v167
	v_add_f32_e32 v121, v164, v165
	v_add_f32_e32 v114, v114, v115
	v_add_f32_e32 v115, v118, v119
	v_add_f32_e32 v120, v121, v120
	v_add_f32_e32 v121, v162, v163
	v_add_f32_e32 v122, v158, v159
	v_add_f32_e32 v114, v115, v114
	v_add_f32_e32 v115, v116, v117
	v_add_f32_e32 v112, v112, v113
	v_add_f32_e32 v121, v122, v121
	v_add_f32_e32 v112, v112, v115
	v_add_f32_e32 v120, v121, v120
	v_add_f32_e32 v112, v112, v114
	v_add_f32_e32 v112, v120, v112
	ds_bpermute_b32 v113, v169, v112
	s_waitcnt lgkmcnt(0)
	v_add_f32_e32 v112, v112, v113
	ds_bpermute_b32 v113, v155, v112
	s_and_saveexec_b64 s[0:1], s[46:47]
	s_cbranch_execz .LBB0_472
	s_waitcnt lgkmcnt(0)
	v_add_f32_e32 v114, v112, v113
	v_lshlrev_b64 v[112:113], 6, v[142:143]
	v_lshl_add_u64 v[112:113], s[6:7], 0, v[112:113]
	v_lshl_add_u64 v[112:113], s[42:43], 2, v[112:113]
	s_lshl_b32 s94, s35, 2
	v_lshl_add_u64 v[112:113], v[112:113], 0, s[94:95]
	global_store_dword v[112:113], v114, off

; DI float rowscale(const float* ss, int row) {
;     const f32x4* p = (const f32x4*)(ss + (size_t)row * 16);
;     const f32x4 a = p[0], b = p[1], c = p[2], d = p[3];
;     const float s = (((a.x + a.y) + (a.z + a.w)) + ((b.x + b.y) + (b.z + b.w))) + (((c.x + c.y) + (c.z + c.w)) + ((d.x + d.y) + (d.z + d.w)));
;     return rsqrtf(s * (1.0f / 1024.0f) + EPS);
; }
; DI void rowscales8(const float* ss, int rowbase, int fr, int fq, float (&r)[2][4]) {
;     const int lane = fq * 16 + fr;
;     const float rA = rowscale(ss, rowbase + lane), rB = rowscale(ss, rowbase + 128 + lane);
; #pragma unroll
;     for (int m = 0; m < 4; ++m) { r[0][m] = __shfl(rA, m * 16 + fr); r[1][m] = __shfl(rB, m * 16 + fr); }
; }
;     DI void operator()(const pg8::f32x4 (&acc)[2][2][4][2], const pg8::Unit& u, int wr, int wc, int fr, int fq) const {
;         const int row0 = u.pm * 256 + wr * 64 + fr, col0 = u.pn * 128 + wc * 32 + 8 * fq;
;         float rs[2][4]; rowscales8(ss, u.pm * 256 + wr * 64, fr, fq, rs);
; #pragma unroll
;         for (int ai = 0; ai < 2; ++ai)
; #pragma unroll
;             for (int m = 0; m < 4; ++m) {
;                 const int row = row0 + ai * 128 + m * 16; const float r = rs[ai][m];
;                 float hv[8];
; #pragma unroll
;                 for (int n = 0; n < 2; ++n) { const pg8::f32x4 g = acc[ai][0][m][n] * r, uu = acc[ai][1][m][n] * r;
; #pragma unroll
;                     for (int e = 0; e < 4; ++e) hv[4 * n + e] = g[e] * __frcp_rn(1.0f + __expf(-g[e])) * uu[e]; }
.LBB0_520:
	s_lshl_b32 s9, s16, 8
	s_add_i32 s9, s9, s48
	v_or_b32_e32 v154, s9, v143
	v_ashrrev_i32_e32 v155, 31, v154
	v_lshlrev_b64 v[154:155], 6, v[154:155]
	v_lshl_add_u64 v[158:159], s[4:5], 0, v[154:155]
	global_load_dwordx4 v[154:157], v[158:159], off offset:16
	global_load_dwordx4 v[162:165], v[158:159], off offset:48
	global_load_dwordx4 v[166:169], v[158:159], off
	global_load_dwordx4 v[170:173], v[158:159], off offset:32
	v_add_u32_e32 v232, s9, v145
	v_ashrrev_i32_e32 v233, 31, v232
	v_lshlrev_b64 v[232:233], 6, v[232:233]
	v_lshl_add_u64 v[230:231], s[4:5], 0, v[232:233]
	global_load_dwordx4 v[214:217], v[230:231], off offset:16
	global_load_dwordx4 v[218:221], v[230:231], off offset:48
	global_load_dwordx4 v[222:225], v[230:231], off
	global_load_dwordx4 v[226:229], v[230:231], off offset:32
	s_mov_b32 s16, 0x3a800000
	v_lshl_or_b32 v152, s17, 7, v147
	v_or_b32_e32 v151, s9, v139
	s_mul_i32 s11, s88, 56
	s_waitcnt vmcnt(4)
	v_mov_b32_e32 v158, v166
	v_mov_b32_e32 v159, v170
	v_mov_b32_e32 v170, v167
	v_mov_b32_e32 v166, v168
	v_mov_b32_e32 v167, v172
	v_mov_b32_e32 v172, v169
	v_pk_add_f32 v[158:159], v[158:159], v[170:171]
	v_pk_add_f32 v[166:167], v[166:167], v[172:173]
	v_pk_add_f32 v[158:159], v[158:159], v[166:167]
	v_mov_b32_e32 v166, v154
	v_mov_b32_e32 v167, v162
	v_mov_b32_e32 v162, v155
	v_pk_add_f32 v[154:155], v[166:167], v[162:163]
	v_mov_b32_e32 v162, v156
	v_mov_b32_e32 v163, v164
	v_mov_b32_e32 v164, v157
	v_pk_add_f32 v[156:157], v[162:163], v[164:165]
	v_pk_add_f32 v[154:155], v[154:155], v[156:157]
	v_pk_add_f32 v[158:159], v[158:159], v[154:155]
	s_waitcnt vmcnt(0)
	v_mov_b64_e32 v[154:155], v[214:215]
	v_mov_b64_e32 v[156:157], v[216:217]
	v_mov_b64_e32 v[162:163], v[218:219]
	v_mov_b64_e32 v[164:165], v[220:221]
	v_mov_b64_e32 v[166:167], v[222:223]
	v_mov_b64_e32 v[168:169], v[224:225]
	v_mov_b64_e32 v[170:171], v[226:227]
	v_mov_b64_e32 v[172:173], v[228:229]
	s_movk_i32 s9, 0x1600
	v_mov_b32_e32 v174, v166
	v_mov_b32_e32 v175, v170
	v_mov_b32_e32 v170, v167
	v_pk_add_f32 v[166:167], v[174:175], v[170:171]
	v_mov_b32_e32 v170, v168
	v_mov_b32_e32 v171, v172
	v_mov_b32_e32 v172, v169
	v_pk_add_f32 v[168:169], v[170:171], v[172:173]
	v_pk_add_f32 v[166:167], v[166:167], v[168:169]
	v_mov_b32_e32 v168, v154
	v_mov_b32_e32 v169, v162
	v_mov_b32_e32 v162, v155
	v_pk_add_f32 v[154:155], v[168:169], v[162:163]
	v_mov_b32_e32 v162, v156
	v_mov_b32_e32 v163, v164
	v_mov_b32_e32 v164, v157
	v_pk_add_f32 v[156:157], v[162:163], v[164:165]
	v_pk_add_f32 v[154:155], v[154:155], v[156:157]
	v_mov_b32_e32 v157, v158
	v_pk_add_f32 v[154:155], v[166:167], v[154:155]
	v_mov_b32_e32 v156, v154
	v_mov_b32_e32 v158, v155
	v_pk_add_f32 v[154:155], v[156:157], v[158:159]
	v_pk_fma_f32 v[154:155], v[154:155], s[16:17], v[176:177] op_sel_hi:[1,0,0]
	v_mul_f32_e32 v138, 0x4b800000, v155
	v_cmp_gt_f32_e64 s[42:43], s39, v155
	v_cmp_gt_f32_e32 vcc, s39, v154
	s_nop 0
	v_cndmask_b32_e64 v138, v155, v138, s[42:43]
	v_rsq_f32_e32 v138, v138
	s_nop 0
	v_mul_f32_e32 v140, 0x45800000, v138
	v_cndmask_b32_e64 v138, v138, v140, s[42:43]
	v_mul_f32_e32 v140, 0x4b800000, v154
	v_cndmask_b32_e32 v140, v154, v140, vcc
	v_rsq_f32_e32 v140, v140
	s_nop 0
	v_mul_f32_e32 v142, 0x45800000, v140
	v_cndmask_b32_e32 v153, v140, v142, vcc
	v_and_or_b32 v140, v177, 64, v139
	v_lshlrev_b32_e32 v155, 2, v140
	ds_bpermute_b32 v154, v155, v138
	ds_bpermute_b32 v144, v155, v153
	ds_bpermute_b32 v150, v155, v138 offset:64
	ds_bpermute_b32 v142, v155, v153 offset:64
	ds_bpermute_b32 v148, v155, v138 offset:128
	s_waitcnt lgkmcnt(4)
	v_pk_mul_f32 v[124:125], v[124:125], v[154:155] op_sel_hi:[1,0]
	ds_bpermute_b32 v140, v155, v153 offset:128
	ds_bpermute_b32 v146, v155, v138 offset:192
	ds_bpermute_b32 v138, v155, v153 offset:192
	v_mul_f32_e32 v155, 0xbfb8aa3b, v124
	v_exp_f32_e32 v156, v155
	v_mul_f32_e32 v155, 0xbfb8aa3b, v125
	v_exp_f32_e32 v157, v155
	v_ashrrev_i32_e32 v153, 31, v152
	s_waitcnt lgkmcnt(5)
	v_pk_mul_f32 v[108:109], v[108:109], v[150:151] op_sel_hi:[1,0]
	v_pk_mul_f32 v[104:105], v[104:105], v[150:151] op_sel_hi:[1,0]
	v_pk_add_f32 v[156:157], v[156:157], 1.0 op_sel_hi:[1,0]
	v_pk_mul_f32 v[106:107], v[106:107], v[150:151] op_sel_hi:[1,0]
	v_pk_mul_f32 v[100:101], v[100:101], v[150:151] op_sel_hi:[1,0]
	v_pk_mul_f32 v[96:97], v[96:97], v[150:151] op_sel_hi:[1,0]
	v_pk_mul_f32 v[98:99], v[98:99], v[150:151] op_sel_hi:[1,0]
	v_rcp_f32_e32 v157, v157
	s_waitcnt lgkmcnt(3)
	v_pk_mul_f32 v[92:93], v[92:93], v[148:149] op_sel_hi:[1,0]
	v_pk_mul_f32 v[88:89], v[88:89], v[148:149] op_sel_hi:[1,0]
	v_pk_mul_f32 v[90:91], v[90:91], v[148:149] op_sel_hi:[1,0]
	v_rcp_f32_e32 v156, v156
	s_nop 0
	v_pk_mul_f32 v[124:125], v[124:125], v[156:157]
	v_pk_mul_f32 v[120:121], v[120:121], v[154:155] op_sel_hi:[1,0]
	v_pk_mul_f32 v[84:85], v[84:85], v[148:149] op_sel_hi:[1,0]
	v_pk_mul_f32 v[120:121], v[120:121], v[124:125]
	v_pk_mul_f32 v[124:125], v[126:127], v[154:155] op_sel_hi:[1,0]
	v_pk_mul_f32 v[80:81], v[80:81], v[148:149] op_sel_hi:[1,0]
	v_mul_f32_e32 v126, 0xbfb8aa3b, v124
	v_mul_f32_e32 v127, 0xbfb8aa3b, v125
	v_exp_f32_e32 v126, v126
	v_exp_f32_e32 v127, v127
	v_pk_mul_f32 v[82:83], v[82:83], v[148:149] op_sel_hi:[1,0]
	s_waitcnt lgkmcnt(1)
; DI unsigned pk2(float lo, float hi) { const f32x2_t v = {lo, hi}; const bf16x2_t b = __builtin_convertvector(v, bf16x2_t); return __builtin_bit_cast(unsigned, b); }
;     DI void operator()(const pg8::f32x4 (&acc)[2][2][4][2], const pg8::Unit& u, int wr, int wc, int fr, int fq) const {
;     ...
;         for (int ai = 0; ai < 2; ++ai)
; #pragma unroll
;             for (int m = 0; m < 4; ++m) {
;                 const int row = row0 + ai * 128 + m * 16; const float r = rs[ai][m];
;                 float hv[8];
; #pragma unroll
;                 for (int n = 0; n < 2; ++n) { const pg8::f32x4 g = acc[ai][0][m][n] * r, uu = acc[ai][1][m][n] * r;
; #pragma unroll
;                     for (int e = 0; e < 4; ++e) hv[4 * n + e] = g[e] * __frcp_rn(1.0f + __expf(-g[e])) * uu[e]; }
;                 u32x4 w; w.x = pk2(hv[0], hv[1]); w.y = pk2(hv[2], hv[3]); w.z = pk2(hv[4], hv[5]); w.w = pk2(hv[6], hv[7]);
;                 *(u32x4*)(H + (size_t)row * DFF + col0) = w;
;             }
	v_pk_mul_f32 v[76:77], v[76:77], v[146:147] op_sel_hi:[1,0]
	v_pk_mul_f32 v[72:73], v[72:73], v[146:147] op_sel_hi:[1,0]
	v_pk_add_f32 v[126:127], v[126:127], 1.0 op_sel_hi:[1,0]
	v_pk_mul_f32 v[74:75], v[74:75], v[146:147] op_sel_hi:[1,0]
	v_pk_mul_f32 v[68:69], v[68:69], v[146:147] op_sel_hi:[1,0]
	v_pk_mul_f32 v[64:65], v[64:65], v[146:147] op_sel_hi:[1,0]
	v_pk_mul_f32 v[66:67], v[66:67], v[146:147] op_sel_hi:[1,0]
	v_rcp_f32_e32 v127, v127
	v_pk_mul_f32 v[60:61], v[60:61], v[144:145] op_sel_hi:[1,0]
	v_pk_mul_f32 v[56:57], v[56:57], v[144:145] op_sel_hi:[1,0]
	v_pk_mul_f32 v[58:59], v[58:59], v[144:145] op_sel_hi:[1,0]
	v_rcp_f32_e32 v126, v126
	s_nop 0
	v_pk_mul_f32 v[124:125], v[124:125], v[126:127]
	v_pk_mul_f32 v[122:123], v[122:123], v[154:155] op_sel_hi:[1,0]
	v_pk_mul_f32 v[116:117], v[116:117], v[154:155] op_sel_hi:[1,0]
	v_pk_mul_f32 v[122:123], v[122:123], v[124:125]
	v_mul_f32_e32 v124, 0xbfb8aa3b, v116
	v_mul_f32_e32 v125, 0xbfb8aa3b, v117
	v_exp_f32_e32 v124, v124
	v_exp_f32_e32 v125, v125
	v_pk_mul_f32 v[52:53], v[52:53], v[144:145] op_sel_hi:[1,0]
	v_pk_mul_f32 v[48:49], v[48:49], v[144:145] op_sel_hi:[1,0]
	v_pk_mul_f32 v[50:51], v[50:51], v[144:145] op_sel_hi:[1,0]
	v_pk_add_f32 v[124:125], v[124:125], 1.0 op_sel_hi:[1,0]
	v_pk_mul_f32 v[44:45], v[44:45], v[142:143] op_sel_hi:[1,0]
	v_pk_mul_f32 v[40:41], v[40:41], v[142:143] op_sel_hi:[1,0]
	v_pk_mul_f32 v[42:43], v[42:43], v[142:143] op_sel_hi:[1,0]
	v_pk_mul_f32 v[36:37], v[36:37], v[142:143] op_sel_hi:[1,0]
	v_rcp_f32_e32 v125, v125
	v_pk_mul_f32 v[32:33], v[32:33], v[142:143] op_sel_hi:[1,0]
	v_pk_mul_f32 v[34:35], v[34:35], v[142:143] op_sel_hi:[1,0]
	v_pk_mul_f32 v[28:29], v[28:29], v[140:141] op_sel_hi:[1,0]
	v_rcp_f32_e32 v124, v124
	s_nop 0
	v_pk_mul_f32 v[116:117], v[116:117], v[124:125]
	v_pk_mul_f32 v[112:113], v[112:113], v[154:155] op_sel_hi:[1,0]
	v_pk_mul_f32 v[24:25], v[24:25], v[140:141] op_sel_hi:[1,0]
	v_pk_mul_f32 v[112:113], v[112:113], v[116:117]
	v_pk_mul_f32 v[116:117], v[118:119], v[154:155] op_sel_hi:[1,0]
	v_pk_mul_f32 v[26:27], v[26:27], v[140:141] op_sel_hi:[1,0]
	v_mul_f32_e32 v118, 0xbfb8aa3b, v116
	v_mul_f32_e32 v119, 0xbfb8aa3b, v117
	v_exp_f32_e32 v118, v118
	v_exp_f32_e32 v119, v119
	v_pk_mul_f32 v[20:21], v[20:21], v[140:141] op_sel_hi:[1,0]
	v_pk_mul_f32 v[16:17], v[16:17], v[140:141] op_sel_hi:[1,0]
	v_pk_mul_f32 v[18:19], v[18:19], v[140:141] op_sel_hi:[1,0]
	v_pk_add_f32 v[118:119], v[118:119], 1.0 op_sel_hi:[1,0]
	s_waitcnt lgkmcnt(0)
	v_pk_mul_f32 v[12:13], v[12:13], v[138:139] op_sel_hi:[1,0]
	v_pk_mul_f32 v[8:9], v[8:9], v[138:139] op_sel_hi:[1,0]
	v_pk_mul_f32 v[10:11], v[10:11], v[138:139] op_sel_hi:[1,0]
	v_pk_mul_f32 v[4:5], v[4:5], v[138:139] op_sel_hi:[1,0]
	v_rcp_f32_e32 v119, v119
	v_pk_mul_f32 v[0:1], v[0:1], v[138:139] op_sel_hi:[1,0]
	v_pk_mul_f32 v[2:3], v[2:3], v[138:139] op_sel_hi:[1,0]
	v_rcp_f32_e32 v118, v118
	s_nop 0
	v_pk_mul_f32 v[116:117], v[116:117], v[118:119]
	v_pk_mul_f32 v[114:115], v[114:115], v[154:155] op_sel_hi:[1,0]
	v_cvt_pk_bf16_f32 v118, v112, v113
	v_pk_mul_f32 v[114:115], v[114:115], v[116:117]
	v_mov_b64_e32 v[112:113], s[82:83]
	v_cvt_pk_bf16_f32 v116, v120, v121
	v_cvt_pk_bf16_f32 v119, v114, v115
	v_mad_i64_i32 v[120:121], s[16:17], v151, s9, v[112:113]
	v_lshlrev_b64 v[114:115], 1, v[152:153]
	v_cvt_pk_bf16_f32 v117, v122, v123
	v_lshl_add_u64 v[120:121], v[120:121], 0, v[114:115]
	global_store_dwordx4 v[120:121], v[116:119], off
	s_nop 1
	v_mul_f32_e32 v116, 0xbfb8aa3b, v108
	v_mul_f32_e32 v117, 0xbfb8aa3b, v109
	v_exp_f32_e32 v116, v116
	v_exp_f32_e32 v117, v117
	s_nop 0
	v_pk_add_f32 v[116:117], v[116:117], 1.0 op_sel_hi:[1,0]
	v_rcp_f32_e32 v117, v117
	v_rcp_f32_e32 v116, v116
	s_nop 0
	v_pk_mul_f32 v[108:109], v[108:109], v[116:117]
	v_pk_mul_f32 v[104:105], v[104:105], v[108:109]
	v_pk_mul_f32 v[108:109], v[110:111], v[150:151] op_sel_hi:[1,0]
	v_mul_f32_e32 v110, 0xbfb8aa3b, v108
	v_mul_f32_e32 v111, 0xbfb8aa3b, v109
	v_exp_f32_e32 v110, v110
	v_exp_f32_e32 v111, v111
	s_nop 0
	v_pk_add_f32 v[110:111], v[110:111], 1.0 op_sel_hi:[1,0]
	v_rcp_f32_e32 v111, v111
	v_rcp_f32_e32 v110, v110
	s_nop 0
	v_pk_mul_f32 v[108:109], v[108:109], v[110:111]
	v_pk_mul_f32 v[106:107], v[106:107], v[108:109]
	v_mul_f32_e32 v108, 0xbfb8aa3b, v100
	v_mul_f32_e32 v109, 0xbfb8aa3b, v101
	v_exp_f32_e32 v108, v108
	v_exp_f32_e32 v109, v109
	s_nop 0
	v_pk_add_f32 v[108:109], v[108:109], 1.0 op_sel_hi:[1,0]
	v_rcp_f32_e32 v109, v109
	v_rcp_f32_e32 v108, v108
	s_nop 0
	v_pk_mul_f32 v[100:101], v[100:101], v[108:109]
	v_pk_mul_f32 v[100:101], v[96:97], v[100:101]
	v_pk_mul_f32 v[96:97], v[102:103], v[150:151] op_sel_hi:[1,0]
	v_mul_f32_e32 v102, 0xbfb8aa3b, v96
	v_mul_f32_e32 v103, 0xbfb8aa3b, v97
	v_exp_f32_e32 v102, v102
	v_exp_f32_e32 v103, v103
	s_nop 0
	v_pk_add_f32 v[102:103], v[102:103], 1.0 op_sel_hi:[1,0]
	v_rcp_f32_e32 v103, v103
	v_rcp_f32_e32 v102, v102
	s_nop 0
	v_pk_mul_f32 v[96:97], v[96:97], v[102:103]
	v_or_b32_e32 v108, 16, v151
	v_pk_mul_f32 v[102:103], v[98:99], v[96:97]
	v_cvt_pk_bf16_f32 v98, v100, v101
	v_mad_i64_i32 v[100:101], s[16:17], v108, s9, v[112:113]
	v_cvt_pk_bf16_f32 v96, v104, v105
	v_cvt_pk_bf16_f32 v97, v106, v107
	v_cvt_pk_bf16_f32 v99, v102, v103
	v_lshl_add_u64 v[100:101], v[100:101], 0, v[114:115]
	global_store_dwordx4 v[100:101], v[96:99], off
	s_nop 1
	v_mul_f32_e32 v96, 0xbfb8aa3b, v92
	v_mul_f32_e32 v97, 0xbfb8aa3b, v93
	v_exp_f32_e32 v96, v96
	v_exp_f32_e32 v97, v97
	s_nop 0
	v_pk_add_f32 v[96:97], v[96:97], 1.0 op_sel_hi:[1,0]
	v_rcp_f32_e32 v97, v97
	v_rcp_f32_e32 v96, v96
	s_nop 0
	v_pk_mul_f32 v[92:93], v[92:93], v[96:97]
	v_pk_mul_f32 v[88:89], v[88:89], v[92:93]
; DI unsigned pk2(float lo, float hi) { const f32x2_t v = {lo, hi}; const bf16x2_t b = __builtin_convertvector(v, bf16x2_t); return __builtin_bit_cast(unsigned, b); }
;     DI void operator()(const pg8::f32x4 (&acc)[2][2][4][2], const pg8::Unit& u, int wr, int wc, int fr, int fq) const {
;     ...
;         for (int ai = 0; ai < 2; ++ai)
; #pragma unroll
;             for (int m = 0; m < 4; ++m) {
;                 const int row = row0 + ai * 128 + m * 16; const float r = rs[ai][m];
;                 float hv[8];
; #pragma unroll
;                 for (int n = 0; n < 2; ++n) { const pg8::f32x4 g = acc[ai][0][m][n] * r, uu = acc[ai][1][m][n] * r;
; #pragma unroll
;                     for (int e = 0; e < 4; ++e) hv[4 * n + e] = g[e] * __frcp_rn(1.0f + __expf(-g[e])) * uu[e]; }
;                 u32x4 w; w.x = pk2(hv[0], hv[1]); w.y = pk2(hv[2], hv[3]); w.z = pk2(hv[4], hv[5]); w.w = pk2(hv[6], hv[7]);
;                 *(u32x4*)(H + (size_t)row * DFF + col0) = w;
;             }
	v_pk_mul_f32 v[92:93], v[94:95], v[148:149] op_sel_hi:[1,0]
	v_mul_f32_e32 v94, 0xbfb8aa3b, v92
	v_mul_f32_e32 v95, 0xbfb8aa3b, v93
	v_exp_f32_e32 v94, v94
	v_exp_f32_e32 v95, v95
	s_nop 0
	v_pk_add_f32 v[94:95], v[94:95], 1.0 op_sel_hi:[1,0]
	v_rcp_f32_e32 v95, v95
	v_rcp_f32_e32 v94, v94
	s_nop 0
	v_pk_mul_f32 v[92:93], v[92:93], v[94:95]
	v_pk_mul_f32 v[90:91], v[90:91], v[92:93]
	v_mul_f32_e32 v92, 0xbfb8aa3b, v84
	v_mul_f32_e32 v93, 0xbfb8aa3b, v85
	v_exp_f32_e32 v92, v92
	v_exp_f32_e32 v93, v93
	s_nop 0
	v_pk_add_f32 v[92:93], v[92:93], 1.0 op_sel_hi:[1,0]
	v_rcp_f32_e32 v93, v93
	v_rcp_f32_e32 v92, v92
	s_nop 0
	v_pk_mul_f32 v[84:85], v[84:85], v[92:93]
	v_pk_mul_f32 v[84:85], v[80:81], v[84:85]
	v_pk_mul_f32 v[80:81], v[86:87], v[148:149] op_sel_hi:[1,0]
	v_mul_f32_e32 v86, 0xbfb8aa3b, v80
	v_mul_f32_e32 v87, 0xbfb8aa3b, v81
	v_exp_f32_e32 v86, v86
	v_exp_f32_e32 v87, v87
	s_nop 0
	v_pk_add_f32 v[86:87], v[86:87], 1.0 op_sel_hi:[1,0]
	v_rcp_f32_e32 v87, v87
	v_rcp_f32_e32 v86, v86
	s_nop 0
	v_pk_mul_f32 v[80:81], v[80:81], v[86:87]
	v_or_b32_e32 v92, 32, v151
	v_pk_mul_f32 v[86:87], v[82:83], v[80:81]
	v_cvt_pk_bf16_f32 v82, v84, v85
	v_mad_i64_i32 v[84:85], s[16:17], v92, s9, v[112:113]
	v_cvt_pk_bf16_f32 v80, v88, v89
	v_cvt_pk_bf16_f32 v81, v90, v91
	v_cvt_pk_bf16_f32 v83, v86, v87
	v_lshl_add_u64 v[84:85], v[84:85], 0, v[114:115]
	global_store_dwordx4 v[84:85], v[80:83], off
	s_nop 1
	v_mul_f32_e32 v80, 0xbfb8aa3b, v76
	v_mul_f32_e32 v81, 0xbfb8aa3b, v77
	v_exp_f32_e32 v80, v80
	v_exp_f32_e32 v81, v81
	s_nop 0
	v_pk_add_f32 v[80:81], v[80:81], 1.0 op_sel_hi:[1,0]
	v_rcp_f32_e32 v81, v81
	v_rcp_f32_e32 v80, v80
	s_nop 0
	v_pk_mul_f32 v[76:77], v[76:77], v[80:81]
	v_pk_mul_f32 v[72:73], v[72:73], v[76:77]
	v_pk_mul_f32 v[76:77], v[78:79], v[146:147] op_sel_hi:[1,0]
	v_mul_f32_e32 v78, 0xbfb8aa3b, v76
	v_mul_f32_e32 v79, 0xbfb8aa3b, v77
	v_exp_f32_e32 v78, v78
	v_exp_f32_e32 v79, v79
	s_nop 0
	v_pk_add_f32 v[78:79], v[78:79], 1.0 op_sel_hi:[1,0]
	v_rcp_f32_e32 v79, v79
	v_rcp_f32_e32 v78, v78
	s_nop 0
	v_pk_mul_f32 v[76:77], v[76:77], v[78:79]
	v_pk_mul_f32 v[74:75], v[74:75], v[76:77]
	v_mul_f32_e32 v76, 0xbfb8aa3b, v68
	v_mul_f32_e32 v77, 0xbfb8aa3b, v69
	v_exp_f32_e32 v76, v76
	v_exp_f32_e32 v77, v77
	s_nop 0
	v_pk_add_f32 v[76:77], v[76:77], 1.0 op_sel_hi:[1,0]
	v_rcp_f32_e32 v77, v77
	v_rcp_f32_e32 v76, v76
	s_nop 0
	v_pk_mul_f32 v[68:69], v[68:69], v[76:77]
	v_pk_mul_f32 v[68:69], v[64:65], v[68:69]
	v_pk_mul_f32 v[64:65], v[70:71], v[146:147] op_sel_hi:[1,0]
	v_mul_f32_e32 v70, 0xbfb8aa3b, v64
	v_mul_f32_e32 v71, 0xbfb8aa3b, v65
	v_exp_f32_e32 v70, v70
	v_exp_f32_e32 v71, v71
	s_nop 0
	v_pk_add_f32 v[70:71], v[70:71], 1.0 op_sel_hi:[1,0]
	v_rcp_f32_e32 v71, v71
	v_rcp_f32_e32 v70, v70
	s_nop 0
	v_pk_mul_f32 v[64:65], v[64:65], v[70:71]
	v_or_b32_e32 v76, 48, v151
	v_pk_mul_f32 v[70:71], v[66:67], v[64:65]
	v_cvt_pk_bf16_f32 v66, v68, v69
	v_mad_i64_i32 v[68:69], s[16:17], v76, s9, v[112:113]
	v_cvt_pk_bf16_f32 v64, v72, v73
	v_cvt_pk_bf16_f32 v65, v74, v75
	v_cvt_pk_bf16_f32 v67, v70, v71
	v_lshl_add_u64 v[68:69], v[68:69], 0, v[114:115]
	global_store_dwordx4 v[68:69], v[64:67], off
	s_nop 1
	v_mul_f32_e32 v64, 0xbfb8aa3b, v60
	v_mul_f32_e32 v65, 0xbfb8aa3b, v61
	v_exp_f32_e32 v64, v64
	v_exp_f32_e32 v65, v65
	v_add_u32_e32 v66, 0x80, v151
	v_pk_add_f32 v[64:65], v[64:65], 1.0 op_sel_hi:[1,0]
	v_rcp_f32_e32 v65, v65
	v_rcp_f32_e32 v64, v64
	s_nop 0
	v_pk_mul_f32 v[60:61], v[60:61], v[64:65]
	v_pk_mul_f32 v[56:57], v[56:57], v[60:61]
	v_pk_mul_f32 v[60:61], v[62:63], v[144:145] op_sel_hi:[1,0]
	v_mul_f32_e32 v62, 0xbfb8aa3b, v60
	v_mul_f32_e32 v63, 0xbfb8aa3b, v61
	v_exp_f32_e32 v62, v62
	v_exp_f32_e32 v63, v63
	s_nop 0
	v_pk_add_f32 v[62:63], v[62:63], 1.0 op_sel_hi:[1,0]
	v_rcp_f32_e32 v63, v63
	v_rcp_f32_e32 v62, v62
	s_nop 0
	v_pk_mul_f32 v[60:61], v[60:61], v[62:63]
	v_pk_mul_f32 v[58:59], v[58:59], v[60:61]
	v_mul_f32_e32 v60, 0xbfb8aa3b, v52
	v_mul_f32_e32 v61, 0xbfb8aa3b, v53
	v_exp_f32_e32 v60, v60
	v_exp_f32_e32 v61, v61
	s_nop 0
	v_pk_add_f32 v[60:61], v[60:61], 1.0 op_sel_hi:[1,0]
	v_rcp_f32_e32 v61, v61
	v_rcp_f32_e32 v60, v60
	s_nop 0
	v_pk_mul_f32 v[52:53], v[52:53], v[60:61]
	v_pk_mul_f32 v[52:53], v[48:49], v[52:53]
	v_pk_mul_f32 v[48:49], v[54:55], v[144:145] op_sel_hi:[1,0]
	v_mul_f32_e32 v54, 0xbfb8aa3b, v48
	v_mul_f32_e32 v55, 0xbfb8aa3b, v49
	v_exp_f32_e32 v54, v54
	v_exp_f32_e32 v55, v55
	s_nop 0
	v_pk_add_f32 v[54:55], v[54:55], 1.0 op_sel_hi:[1,0]
	v_rcp_f32_e32 v55, v55
	v_rcp_f32_e32 v54, v54
	s_nop 0
	v_pk_mul_f32 v[48:49], v[48:49], v[54:55]
	v_pk_mul_f32 v[54:55], v[50:51], v[48:49]
	v_cvt_pk_bf16_f32 v50, v52, v53
	v_mad_i64_i32 v[52:53], s[16:17], v66, s9, v[112:113]
	v_cvt_pk_bf16_f32 v48, v56, v57
	v_cvt_pk_bf16_f32 v49, v58, v59
	v_cvt_pk_bf16_f32 v51, v54, v55
	v_lshl_add_u64 v[52:53], v[52:53], 0, v[114:115]
	global_store_dwordx4 v[52:53], v[48:51], off
	s_nop 1
	v_mul_f32_e32 v48, 0xbfb8aa3b, v44
	v_mul_f32_e32 v49, 0xbfb8aa3b, v45
	v_exp_f32_e32 v48, v48
	v_exp_f32_e32 v49, v49
	s_nop 0
	v_pk_add_f32 v[48:49], v[48:49], 1.0 op_sel_hi:[1,0]
	v_rcp_f32_e32 v49, v49
; #define PG8_BAR __builtin_amdgcn_s_barrier()
; DI unsigned pk2(float lo, float hi) { const f32x2_t v = {lo, hi}; const bf16x2_t b = __builtin_convertvector(v, bf16x2_t); return __builtin_bit_cast(unsigned, b); }
; template <class Epi, class Sched, bool ALIGN_EPI = false, bool SP2 = false>
; __device__ __forceinline__ void gemm_phase(PG8_LAS unsigned char* lds, const Gemm g, const Sched& S, const Epi& E, const int tid) {
;     ...
;         if constexpr (ALIGN_EPI) { if (wr == 0) PG8_BAR; }
;         if constexpr (!Epi::AFTER_DRAIN) { E(acc, cur, wr, wc, fr, fq); S.done(cur); }
;         if (!has_next) break;
; #pragma unroll
;         for (int a = 0; a < 2; ++a)
; #pragma unroll
;             for (int b = 0; b < 2; ++b)
; #pragma unroll
;                 for (int m = 0; m < 4; ++m)
; #pragma unroll
;                     for (int n = 0; n < 2; ++n) acc[a][b][m][n] = (f32x4){0.f, 0.f, 0.f, 0.f};
;         cur = nxt; cA = nA; cB = nB; ++ui;
;         if constexpr (ALIGN_EPI) { if (wr == 1) PG8_BAR; }
;     }
;     DI void operator()(const pg8::f32x4 (&acc)[2][2][4][2], const pg8::Unit& u, int wr, int wc, int fr, int fq) const {
;     ...
;         for (int ai = 0; ai < 2; ++ai)
; #pragma unroll
;             for (int m = 0; m < 4; ++m) {
;                 const int row = row0 + ai * 128 + m * 16; const float r = rs[ai][m];
;                 float hv[8];
; #pragma unroll
;                 for (int n = 0; n < 2; ++n) { const pg8::f32x4 g = acc[ai][0][m][n] * r, uu = acc[ai][1][m][n] * r;
; #pragma unroll
;                     for (int e = 0; e < 4; ++e) hv[4 * n + e] = g[e] * __frcp_rn(1.0f + __expf(-g[e])) * uu[e]; }
;                 u32x4 w; w.x = pk2(hv[0], hv[1]); w.y = pk2(hv[2], hv[3]); w.z = pk2(hv[4], hv[5]); w.w = pk2(hv[6], hv[7]);
;                 *(u32x4*)(H + (size_t)row * DFF + col0) = w;
;             }
	v_rcp_f32_e32 v48, v48
	s_nop 0
	v_pk_mul_f32 v[44:45], v[44:45], v[48:49]
	v_pk_mul_f32 v[40:41], v[40:41], v[44:45]
	v_pk_mul_f32 v[44:45], v[46:47], v[142:143] op_sel_hi:[1,0]
	v_mul_f32_e32 v46, 0xbfb8aa3b, v44
	v_mul_f32_e32 v47, 0xbfb8aa3b, v45
	v_exp_f32_e32 v46, v46
	v_exp_f32_e32 v47, v47
	s_nop 0
	v_pk_add_f32 v[46:47], v[46:47], 1.0 op_sel_hi:[1,0]
	v_rcp_f32_e32 v47, v47
	v_rcp_f32_e32 v46, v46
	s_nop 0
	v_pk_mul_f32 v[44:45], v[44:45], v[46:47]
	v_pk_mul_f32 v[42:43], v[42:43], v[44:45]
	v_mul_f32_e32 v44, 0xbfb8aa3b, v36
	v_mul_f32_e32 v45, 0xbfb8aa3b, v37
	v_exp_f32_e32 v44, v44
	v_exp_f32_e32 v45, v45
	s_nop 0
	v_pk_add_f32 v[44:45], v[44:45], 1.0 op_sel_hi:[1,0]
	v_rcp_f32_e32 v45, v45
	v_rcp_f32_e32 v44, v44
	s_nop 0
	v_pk_mul_f32 v[36:37], v[36:37], v[44:45]
	v_pk_mul_f32 v[36:37], v[32:33], v[36:37]
	v_pk_mul_f32 v[32:33], v[38:39], v[142:143] op_sel_hi:[1,0]
	v_mul_f32_e32 v38, 0xbfb8aa3b, v32
	v_mul_f32_e32 v39, 0xbfb8aa3b, v33
	v_exp_f32_e32 v38, v38
	v_exp_f32_e32 v39, v39
	s_nop 0
	v_pk_add_f32 v[38:39], v[38:39], 1.0 op_sel_hi:[1,0]
	v_rcp_f32_e32 v39, v39
	v_rcp_f32_e32 v38, v38
	s_nop 0
	v_pk_mul_f32 v[32:33], v[32:33], v[38:39]
	v_add_u32_e32 v44, 0x90, v151
	v_pk_mul_f32 v[38:39], v[34:35], v[32:33]
	v_cvt_pk_bf16_f32 v34, v36, v37
	v_mad_i64_i32 v[36:37], s[16:17], v44, s9, v[112:113]
	v_cvt_pk_bf16_f32 v32, v40, v41
	v_cvt_pk_bf16_f32 v33, v42, v43
	v_cvt_pk_bf16_f32 v35, v38, v39
	v_lshl_add_u64 v[36:37], v[36:37], 0, v[114:115]
	global_store_dwordx4 v[36:37], v[32:35], off
	s_nop 1
	v_mul_f32_e32 v32, 0xbfb8aa3b, v28
	v_mul_f32_e32 v33, 0xbfb8aa3b, v29
	v_exp_f32_e32 v32, v32
	v_exp_f32_e32 v33, v33
	s_nop 0
	v_pk_add_f32 v[32:33], v[32:33], 1.0 op_sel_hi:[1,0]
	v_rcp_f32_e32 v33, v33
	v_rcp_f32_e32 v32, v32
	s_nop 0
	v_pk_mul_f32 v[28:29], v[28:29], v[32:33]
	v_pk_mul_f32 v[24:25], v[24:25], v[28:29]
	v_pk_mul_f32 v[28:29], v[30:31], v[140:141] op_sel_hi:[1,0]
	v_mul_f32_e32 v30, 0xbfb8aa3b, v28
	v_mul_f32_e32 v31, 0xbfb8aa3b, v29
	v_exp_f32_e32 v30, v30
	v_exp_f32_e32 v31, v31
	s_nop 0
	v_pk_add_f32 v[30:31], v[30:31], 1.0 op_sel_hi:[1,0]
	v_rcp_f32_e32 v31, v31
	v_rcp_f32_e32 v30, v30
	s_nop 0
	v_pk_mul_f32 v[28:29], v[28:29], v[30:31]
	v_pk_mul_f32 v[26:27], v[26:27], v[28:29]
	v_mul_f32_e32 v28, 0xbfb8aa3b, v20
	v_mul_f32_e32 v29, 0xbfb8aa3b, v21
	v_exp_f32_e32 v28, v28
	v_exp_f32_e32 v29, v29
	s_nop 0
	v_pk_add_f32 v[28:29], v[28:29], 1.0 op_sel_hi:[1,0]
	v_rcp_f32_e32 v29, v29
	v_rcp_f32_e32 v28, v28
	s_nop 0
	v_pk_mul_f32 v[20:21], v[20:21], v[28:29]
	v_pk_mul_f32 v[20:21], v[16:17], v[20:21]
	v_pk_mul_f32 v[16:17], v[22:23], v[140:141] op_sel_hi:[1,0]
	v_mul_f32_e32 v22, 0xbfb8aa3b, v16
	v_mul_f32_e32 v23, 0xbfb8aa3b, v17
	v_exp_f32_e32 v22, v22
	v_exp_f32_e32 v23, v23
	s_nop 0
	v_pk_add_f32 v[22:23], v[22:23], 1.0 op_sel_hi:[1,0]
	v_rcp_f32_e32 v23, v23
	v_rcp_f32_e32 v22, v22
	s_nop 0
	v_pk_mul_f32 v[16:17], v[16:17], v[22:23]
	v_add_u32_e32 v28, 0xa0, v151
	v_pk_mul_f32 v[22:23], v[18:19], v[16:17]
	v_cvt_pk_bf16_f32 v18, v20, v21
	v_mad_i64_i32 v[20:21], s[16:17], v28, s9, v[112:113]
	v_cvt_pk_bf16_f32 v16, v24, v25
	v_cvt_pk_bf16_f32 v17, v26, v27
	v_cvt_pk_bf16_f32 v19, v22, v23
	v_lshl_add_u64 v[20:21], v[20:21], 0, v[114:115]
	global_store_dwordx4 v[20:21], v[16:19], off
	s_nop 1
	v_mul_f32_e32 v16, 0xbfb8aa3b, v12
	v_mul_f32_e32 v17, 0xbfb8aa3b, v13
	v_exp_f32_e32 v16, v16
	v_exp_f32_e32 v17, v17
	s_nop 0
	v_pk_add_f32 v[16:17], v[16:17], 1.0 op_sel_hi:[1,0]
	v_rcp_f32_e32 v17, v17
	v_rcp_f32_e32 v16, v16
	s_nop 0
	v_pk_mul_f32 v[12:13], v[12:13], v[16:17]
	v_pk_mul_f32 v[8:9], v[8:9], v[12:13]
	v_pk_mul_f32 v[12:13], v[14:15], v[138:139] op_sel_hi:[1,0]
	v_mul_f32_e32 v14, 0xbfb8aa3b, v12
	v_mul_f32_e32 v15, 0xbfb8aa3b, v13
	v_exp_f32_e32 v14, v14
	v_exp_f32_e32 v15, v15
	s_nop 0
	v_pk_add_f32 v[14:15], v[14:15], 1.0 op_sel_hi:[1,0]
	v_rcp_f32_e32 v15, v15
	v_rcp_f32_e32 v14, v14
	s_nop 0
	v_pk_mul_f32 v[12:13], v[12:13], v[14:15]
	v_pk_mul_f32 v[10:11], v[10:11], v[12:13]
	v_mul_f32_e32 v12, 0xbfb8aa3b, v4
	v_mul_f32_e32 v13, 0xbfb8aa3b, v5
	v_exp_f32_e32 v12, v12
	v_exp_f32_e32 v13, v13
	s_nop 0
	v_pk_add_f32 v[12:13], v[12:13], 1.0 op_sel_hi:[1,0]
	v_rcp_f32_e32 v13, v13
	v_rcp_f32_e32 v12, v12
	s_nop 0
	v_pk_mul_f32 v[4:5], v[4:5], v[12:13]
	v_pk_mul_f32 v[4:5], v[0:1], v[4:5]
	v_pk_mul_f32 v[0:1], v[6:7], v[138:139] op_sel_hi:[1,0]
	v_mul_f32_e32 v6, 0xbfb8aa3b, v0
	v_mul_f32_e32 v7, 0xbfb8aa3b, v1
	v_exp_f32_e32 v6, v6
	v_exp_f32_e32 v7, v7
	s_nop 0
	v_pk_add_f32 v[6:7], v[6:7], 1.0 op_sel_hi:[1,0]
	v_rcp_f32_e32 v7, v7
	v_rcp_f32_e32 v6, v6
	s_nop 0
	v_pk_mul_f32 v[0:1], v[0:1], v[6:7]
	v_add_u32_e32 v12, 0xb0, v151
	v_pk_mul_f32 v[6:7], v[2:3], v[0:1]
	v_cvt_pk_bf16_f32 v2, v4, v5
	v_mad_i64_i32 v[4:5], s[16:17], v12, s9, v[112:113]
	v_cvt_pk_bf16_f32 v0, v8, v9
	v_cvt_pk_bf16_f32 v1, v10, v11
	v_cvt_pk_bf16_f32 v3, v6, v7
	v_lshl_add_u64 v[4:5], v[4:5], 0, v[114:115]
	s_mov_b64 s[16:17], -1
	s_andn2_b64 vcc, exec, s[40:41]
	global_store_dwordx4 v[4:5], v[0:3], off
	s_cbranch_vccnz .LBB0_509
	s_andn2_b64 vcc, exec, s[2:3]
	s_cbranch_vccnz .LBB0_508
	s_barrier
	s_branch .LBB0_508

; DI float rowscale(const float* ss, int row) {
;     const f32x4* p = (const f32x4*)(ss + (size_t)row * 16);
;     const f32x4 a = p[0], b = p[1], c = p[2], d = p[3];
;     const float s = (((a.x + a.y) + (a.z + a.w)) + ((b.x + b.y) + (b.z + b.w))) + (((c.x + c.y) + (c.z + c.w)) + ((d.x + d.y) + (d.z + d.w)));
;     return rsqrtf(s * (1.0f / 1024.0f) + EPS);
; }
; DI void rowscales8(const float* ss, int rowbase, int fr, int fq, float (&r)[2][4]) {
;     const int lane = fq * 16 + fr;
;     const float rA = rowscale(ss, rowbase + lane), rB = rowscale(ss, rowbase + 128 + lane);
; #pragma unroll
;     for (int m = 0; m < 4; ++m) { r[0][m] = __shfl(rA, m * 16 + fr); r[1][m] = __shfl(rB, m * 16 + fr); }
; }
.LBB0_624:
	s_lshl_b32 s37, s97, 8
	s_andn2_b64 vcc, exec, s[30:31]
	s_add_i32 s37, s37, s81
	s_cbranch_vccnz .LBB0_626
	v_or_b32_e32 v144, s37, v170
	v_ashrrev_i32_e32 v145, 31, v144
	v_lshlrev_b64 v[144:145], 6, v[144:145]
	v_lshl_add_u64 v[156:157], s[4:5], 0, v[144:145]
	global_load_dwordx4 v[144:147], v[156:157], off offset:16
	global_load_dwordx4 v[148:151], v[156:157], off offset:48
	global_load_dwordx4 v[152:155], v[156:157], off
	global_load_dwordx4 v[184:187], v[156:157], off offset:32
	v_or_b32_e32 v238, 0x80, v170
	v_add_u32_e32 v238, s37, v238
	v_ashrrev_i32_e32 v239, 31, v238
	v_lshlrev_b64 v[238:239], 6, v[238:239]
	v_lshl_add_u64 v[236:237], s[4:5], 0, v[238:239]
	global_load_dwordx4 v[220:223], v[236:237], off offset:16
	global_load_dwordx4 v[224:227], v[236:237], off offset:48
	global_load_dwordx4 v[228:231], v[236:237], off
	global_load_dwordx4 v[232:235], v[236:237], off offset:32
	s_mov_b32 s44, 0x3a800000
	s_waitcnt vmcnt(4)
	v_mov_b32_e32 v156, v152
	v_mov_b32_e32 v157, v184
	v_mov_b32_e32 v184, v153
	v_pk_add_f32 v[152:153], v[156:157], v[184:185]
	v_mov_b32_e32 v156, v154
	v_mov_b32_e32 v157, v186
	v_mov_b32_e32 v186, v155
	v_pk_add_f32 v[154:155], v[156:157], v[186:187]
	v_pk_add_f32 v[152:153], v[152:153], v[154:155]
	v_mov_b32_e32 v154, v144
	v_mov_b32_e32 v155, v148
	v_mov_b32_e32 v148, v145
	v_pk_add_f32 v[144:145], v[154:155], v[148:149]
	v_mov_b32_e32 v148, v146
	v_mov_b32_e32 v149, v150
	v_mov_b32_e32 v150, v147
	v_pk_add_f32 v[146:147], v[148:149], v[150:151]
	v_pk_add_f32 v[144:145], v[144:145], v[146:147]
	v_pk_add_f32 v[144:145], v[152:153], v[144:145]
	s_waitcnt vmcnt(0)
	v_mov_b64_e32 v[146:147], v[220:221]
	v_mov_b64_e32 v[148:149], v[222:223]
	v_mov_b64_e32 v[150:151], v[224:225]
	v_mov_b64_e32 v[152:153], v[226:227]
	v_mov_b64_e32 v[154:155], v[228:229]
	v_mov_b64_e32 v[156:157], v[230:231]
	v_mov_b64_e32 v[184:185], v[232:233]
	v_mov_b64_e32 v[186:187], v[234:235]
	v_mov_b32_e32 v178, v154
	v_mov_b32_e32 v179, v184
	v_mov_b32_e32 v184, v155
	v_pk_add_f32 v[154:155], v[178:179], v[184:185]
	v_mov_b32_e32 v178, v156
	v_mov_b32_e32 v179, v186
	v_mov_b32_e32 v186, v157
	v_pk_add_f32 v[156:157], v[178:179], v[186:187]
	v_pk_add_f32 v[154:155], v[154:155], v[156:157]
	v_mov_b32_e32 v156, v146
	v_mov_b32_e32 v157, v150
	v_mov_b32_e32 v150, v147
	v_pk_add_f32 v[146:147], v[156:157], v[150:151]
	v_mov_b32_e32 v150, v148
	v_mov_b32_e32 v151, v152
	v_mov_b32_e32 v152, v149
	v_pk_add_f32 v[148:149], v[150:151], v[152:153]
	v_pk_add_f32 v[146:147], v[146:147], v[148:149]
	v_mov_b32_e32 v149, v144
	v_pk_add_f32 v[146:147], v[154:155], v[146:147]
	v_mov_b32_e32 v148, v146
	v_mov_b32_e32 v144, v147
	v_pk_add_f32 v[144:145], v[148:149], v[144:145]
	v_pk_fma_f32 v[144:145], v[144:145], s[44:45], v[176:177] op_sel_hi:[1,0,0]
	v_mul_f32_e32 v146, 0x4b800000, v145
	v_cmp_gt_f32_e64 s[44:45], s39, v145
	v_cmp_gt_f32_e32 vcc, s39, v144
	s_nop 0
	v_cndmask_b32_e64 v145, v145, v146, s[44:45]
	v_rsq_f32_e32 v145, v145
	s_nop 0
	v_mul_f32_e32 v146, 0x45800000, v145
	v_cndmask_b32_e64 v145, v145, v146, s[44:45]
	v_mul_f32_e32 v146, 0x4b800000, v144
	v_cndmask_b32_e32 v144, v144, v146, vcc
	v_rsq_f32_e32 v144, v144
	s_nop 0
	v_mul_f32_e32 v146, 0x45800000, v144
	v_cndmask_b32_e32 v150, v144, v146, vcc
	v_and_or_b32 v144, v177, 64, v166
	v_lshlrev_b32_e32 v151, 2, v144
	ds_bpermute_b32 v152, v151, v145
	ds_bpermute_b32 v146, v151, v150
	ds_bpermute_b32 v153, v151, v145 offset:64
	ds_bpermute_b32 v147, v151, v150 offset:64
	ds_bpermute_b32 v148, v151, v145 offset:128
	ds_bpermute_b32 v144, v151, v150 offset:128
	ds_bpermute_b32 v149, v151, v145 offset:192
	ds_bpermute_b32 v145, v151, v150 offset:192
	s_branch .LBB0_627
